# LoRA tile balance: 48 prompt-row g tiles deferred to phase 5 on blocks 320..367 (fold-job blocks), 3 LoRA tiles per block in phase 2
# speedup vs baseline: 1.0066x; 1.0025x over previous
.LBB0_273:
	s_cmp_eq_u32 s101, 1
	s_cbranch_scc1 .Llora_ret
	s_add_i32 s34, s34, s94
	s_cmpk_lt_i32 s34, 0x600
	s_cbranch_scc0 .LBB0_435
	s_sub_i32 s0, s34, 0x540
	s_cmpk_lt_u32 s0, 48
	s_cbranch_scc0 .LBB0_274
	s_add_i32 s34, s34, 0xc0

.Llora_call:
	s_sub_i32 s0, s2, 0x140
	s_cmpk_lt_u32 s0, 48
	s_cbranch_scc0 .LBB0_795
	s_waitcnt vmcnt(0) lgkmcnt(0)
	s_barrier
	v_readlane_b32 s80, v242, 17
	v_readlane_b32 s81, v242, 18
	v_readlane_b32 s82, v242, 19
	v_readlane_b32 s83, v242, 20
	v_readlane_b32 s84, v242, 21
	v_readlane_b32 s85, v242, 22
	v_readlane_b32 s86, v242, 23
	v_readlane_b32 s87, v242, 24
	v_readlane_b32 s88, v242, 25
	v_readlane_b32 s89, v242, 26
	v_readlane_b32 s90, v242, 27
	v_readlane_b32 s91, v242, 28
	v_readlane_b32 s92, v242, 29
	v_readlane_b32 s93, v242, 30
	v_readlane_b32 s94, v242, 31
	v_readlane_b32 s95, v242, 32
	s_mov_b32 s101, 1
	s_branch .Llora_pre
